# MLA q GEMM epilogue: row scale loaded once per row, the two rotary table loads of a fragment issued together (one wait instead of three serial round trips per fragment)
# speedup vs baseline: 1.0094x; 1.0094x over previous
.LBB0_2533:
	v_lshl_add_u32 v178, s14, 8, v153
	v_mul_hi_i32 v141, v178, s79
	v_lshrrev_b32_e32 v158, 31, v141
	v_ashrrev_i32_e32 v141, 11, v141
	v_add_u32_e32 v141, v141, v158
	v_lshlrev_b32_e32 v142, 1, v178
	v_mul_i32_i24_e32 v141, 0x2100, v141
	v_ashrrev_i32_e32 v143, 31, v142
	v_sub_u32_e32 v183, v178, v141
	v_add_u32_e32 v141, 0xffffff00, v183
	v_lshl_add_u64 v[142:143], v[142:143], 2, s[40:41]
	v_lshrrev_b32_e32 v181, 6, v141
	global_load_dword v141, v[142:143], off
	v_lshl_or_b32 v140, s12, 8, v161
	v_cmp_lt_i32_e64 s[18:19], s80, v183
	v_and_b32_e32 v182, 15, v183
	s_waitcnt vmcnt(0)
	v_mul_f32_e32 v141, 0x3dd105ec, v141
	v_mul_f32_e32 v180, 0x3fb8aa3b, v141
	v_mov_b32_e32 v210, v180
	v_pk_mul_f32 v[158:159], v[126:127], v[180:181] op_sel_hi:[1,0]
	v_pk_mul_f32 v[126:127], v[124:125], v[180:181] op_sel_hi:[1,0]
	v_mul_hi_i32 v124, v140, s76
	v_lshrrev_b32_e32 v125, 31, v124
	v_lshrrev_b32_e32 v124, 4, v124
	v_add_u32_e32 v124, v124, v125
	v_mul_lo_u32 v124, v124, s52
	v_sub_u32_e32 v124, v140, v124
	v_cmp_lt_i32_e32 vcc, 63, v124
	v_subrev_u32_e32 v179, 64, v124
	s_and_b64 s[0:1], vcc, s[18:19]
	v_lshrrev_b32_e32 v180, 1, v179
	s_and_saveexec_b64 s[12:13], s[0:1]
	s_cbranch_execz .LBB0_2535
	v_cmp_gt_u32_e64 s[0:1], 16, v179
	s_nop 1
	v_cndmask_b32_e64 v124, v182, v181, s[0:1]
	v_lshlrev_b32_e32 v141, 3, v124
	v_and_or_b32 v124, v180, 7, v141
	v_lshlrev_b32_e32 v124, 3, v124
	global_load_dwordx2 v[124:125], v124, s[42:43]
	v_and_or_b32 v141, v180, 6, v141
	v_lshlrev_b32_e32 v141, 3, v141
	global_load_dwordx2 v[200:201], v141, s[42:43] offset:8
	s_waitcnt vmcnt(0)
	v_pk_mul_f32 v[184:185], v[126:127], v[124:125] op_sel:[1,1] op_sel_hi:[0,1]
	v_pk_mul_f32 v[186:187], v[126:127], v[124:125]
	v_pk_fma_f32 v[126:127], v[126:127], v[124:125], v[184:185] op_sel_hi:[1,0,1]
	v_mul_f32_e32 v126, v159, v201
	v_pk_fma_f32 v[188:189], v[158:159], v[200:201], v[126:127] op_sel_hi:[1,1,0] neg_lo:[0,0,1] neg_hi:[0,0,1]
	v_mul_f32_e32 v126, v158, v201
	v_pk_fma_f32 v[124:125], v[158:159], v[200:201], v[126:127] op_sel:[1,0,0] op_sel_hi:[0,1,0]
	v_sub_f32_e32 v126, v186, v184
	v_mov_b32_e32 v158, v188
	v_mov_b32_e32 v159, v124
.LBB0_2535:
	s_or_b64 exec, exec, s[12:13]
	v_mov_b64_e32 v[124:125], s[94:95]
	v_mad_i64_i32 v[124:125], s[0:1], v178, s81, v[124:125]
	v_ashrrev_i32_e32 v141, 31, v140
	v_lshl_add_u64 v[124:125], v[140:141], 1, v[124:125]
	v_cvt_pk_bf16_f32 v126, v126, v127
	v_cvt_pk_bf16_f32 v127, v158, v159
	global_store_dwordx2 v[124:125], v[126:127], off
	v_or_b32_e32 v158, 16, v140
	v_mul_hi_i32 v159, v158, s76
	v_lshlrev_b32_e32 v127, 3, v183
	v_lshrrev_b32_e32 v183, 31, v159
	v_lshrrev_b32_e32 v159, 4, v159
	v_add_u32_e32 v159, v159, v183
	v_mul_lo_u32 v159, v159, s52
	v_sub_u32_e32 v158, v158, v159
	v_and_b32_e32 v127, 0x78, v127
	v_cmp_lt_i32_e64 s[12:13], 63, v158
	v_subrev_u32_e32 v158, 64, v158
	s_and_b64 s[4:5], s[18:19], s[12:13]
	v_mov_b32_e32 v126, v210
	v_pk_mul_f32 v[122:123], v[122:123], v[126:127] op_sel_hi:[1,0]
	v_pk_mul_f32 v[120:121], v[120:121], v[126:127] op_sel_hi:[1,0]
	v_lshrrev_b32_e32 v126, 1, v158
	s_and_saveexec_b64 s[0:1], s[4:5]
	s_cbranch_execz .LBB0_2537
	v_and_or_b32 v158, v126, 7, v127
	v_lshlrev_b32_e32 v158, 3, v158
	global_load_dwordx2 v[158:159], v158, s[42:43]
	v_add_u32_e32 v183, 1, v126
	v_and_or_b32 v183, v183, 7, v127
	v_lshlrev_b32_e32 v183, 3, v183
	global_load_dwordx2 v[200:201], v183, s[42:43]
	s_waitcnt vmcnt(0)
	v_pk_mul_f32 v[184:185], v[120:121], v[158:159] op_sel:[1,1] op_sel_hi:[0,1]
	v_pk_mul_f32 v[186:187], v[120:121], v[158:159]
	v_pk_fma_f32 v[120:121], v[120:121], v[158:159], v[184:185] op_sel_hi:[1,0,1]
	v_mul_f32_e32 v120, v123, v201
	v_pk_fma_f32 v[188:189], v[122:123], v[200:201], v[120:121] op_sel_hi:[1,1,0] neg_lo:[0,0,1] neg_hi:[0,0,1]
	v_mul_f32_e32 v120, v122, v201
	v_pk_fma_f32 v[158:159], v[122:123], v[200:201], v[120:121] op_sel:[1,0,0] op_sel_hi:[0,1,0]
	v_sub_f32_e32 v120, v186, v184
	v_mov_b32_e32 v122, v188
	v_mov_b32_e32 v123, v158
.LBB0_2537:
	s_or_b64 exec, exec, s[0:1]
	v_cvt_pk_bf16_f32 v120, v120, v121
	v_cvt_pk_bf16_f32 v121, v122, v123
	global_store_dwordx2 v[124:125], v[120:121], off offset:32
	v_or_b32_e32 v120, 0x80, v140
	v_mul_hi_i32 v122, v120, s76
	v_lshrrev_b32_e32 v123, 31, v122
	v_lshrrev_b32_e32 v122, 4, v122
	v_add_u32_e32 v122, v122, v123
	v_mul_lo_u32 v122, v122, s52
	v_sub_u32_e32 v120, v120, v122
	v_cmp_lt_i32_e64 s[14:15], 63, v120
	v_subrev_u32_e32 v120, 64, v120
	s_and_b64 s[0:1], s[18:19], s[14:15]
	v_mov_b32_e32 v122, v210
	v_pk_mul_f32 v[118:119], v[118:119], v[122:123] op_sel_hi:[1,0]
	v_pk_mul_f32 v[116:117], v[116:117], v[122:123] op_sel_hi:[1,0]
	v_lshrrev_b32_e32 v121, 1, v120
	s_and_saveexec_b64 s[16:17], s[0:1]
	s_cbranch_execz .LBB0_2539
	v_cmp_gt_u32_e64 s[0:1], 16, v120
	v_add_u32_e32 v159, 1, v121
	s_nop 0
	v_cndmask_b32_e64 v122, v182, v181, s[0:1]
	v_lshlrev_b32_e32 v158, 3, v122
	v_and_or_b32 v122, v121, 7, v158
	v_lshlrev_b32_e32 v122, 3, v122
	global_load_dwordx2 v[122:123], v122, s[42:43]
	v_and_or_b32 v158, v159, 7, v158
	v_lshlrev_b32_e32 v181, 3, v158
	global_load_dwordx2 v[200:201], v181, s[42:43]
	s_waitcnt vmcnt(0)
	v_pk_mul_f32 v[158:159], v[116:117], v[122:123] op_sel:[1,1] op_sel_hi:[0,1]
	v_pk_mul_f32 v[182:183], v[116:117], v[122:123]
	v_pk_fma_f32 v[116:117], v[116:117], v[122:123], v[158:159] op_sel_hi:[1,0,1]
	v_mul_f32_e32 v116, v119, v201
	v_pk_fma_f32 v[184:185], v[118:119], v[200:201], v[116:117] op_sel_hi:[1,1,0] neg_lo:[0,0,1] neg_hi:[0,0,1]
	v_mul_f32_e32 v116, v118, v201
	v_pk_fma_f32 v[122:123], v[118:119], v[200:201], v[116:117] op_sel:[1,0,0] op_sel_hi:[0,1,0]
	v_sub_f32_e32 v116, v182, v158
	v_mov_b32_e32 v118, v184
	v_mov_b32_e32 v119, v122
.LBB0_2539:
	s_or_b64 exec, exec, s[16:17]
	v_cvt_pk_bf16_f32 v116, v116, v117
	v_cvt_pk_bf16_f32 v117, v118, v119
	global_store_dwordx2 v[124:125], v[116:117], off offset:256
	v_or_b32_e32 v117, 0x90, v140
	v_mul_hi_i32 v118, v117, s76
	v_lshrrev_b32_e32 v119, 31, v118
	v_lshrrev_b32_e32 v118, 4, v118
	v_add_u32_e32 v118, v118, v119
	v_mul_lo_u32 v118, v118, s52
	v_sub_u32_e32 v117, v117, v118
	v_cmp_lt_i32_e64 s[16:17], 63, v117
	v_subrev_u32_e32 v117, 64, v117
	s_and_b64 s[4:5], s[18:19], s[16:17]
	v_mov_b32_e32 v116, v210
	v_pk_mul_f32 v[114:115], v[114:115], v[116:117] op_sel_hi:[1,0]
	v_pk_mul_f32 v[112:113], v[112:113], v[116:117] op_sel_hi:[1,0]
	v_lshrrev_b32_e32 v116, 1, v117
	s_and_saveexec_b64 s[0:1], s[4:5]
	s_cbranch_execz .LBB0_2541
	v_and_or_b32 v117, v116, 7, v127
	v_lshlrev_b32_e32 v117, 3, v117
	global_load_dwordx2 v[118:119], v117, s[42:43]
	v_add_u32_e32 v117, 1, v116
	v_and_or_b32 v117, v117, 7, v127
	v_lshlrev_b32_e32 v117, 3, v117
	global_load_dwordx2 v[200:201], v117, s[42:43]
	s_waitcnt vmcnt(0)
	v_pk_mul_f32 v[122:123], v[112:113], v[118:119] op_sel:[1,1] op_sel_hi:[0,1]
	v_pk_mul_f32 v[142:143], v[112:113], v[118:119]
	v_pk_fma_f32 v[112:113], v[112:113], v[118:119], v[122:123] op_sel_hi:[1,0,1]
	v_mul_f32_e32 v112, v115, v201
	v_pk_fma_f32 v[158:159], v[114:115], v[200:201], v[112:113] op_sel_hi:[1,1,0] neg_lo:[0,0,1] neg_hi:[0,0,1]
	v_mul_f32_e32 v112, v114, v201
	v_pk_fma_f32 v[118:119], v[114:115], v[200:201], v[112:113] op_sel:[1,0,0] op_sel_hi:[0,1,0]
	v_sub_f32_e32 v112, v142, v122
	v_mov_b32_e32 v114, v158
	v_mov_b32_e32 v115, v118
.LBB0_2541:
	s_or_b64 exec, exec, s[0:1]
	v_cvt_pk_bf16_f32 v112, v112, v113
	v_cvt_pk_bf16_f32 v113, v114, v115
	v_or_b32_e32 v119, 16, v178
	global_store_dwordx2 v[124:125], v[112:113], off offset:288
	v_lshlrev_b32_e32 v112, 1, v119
	v_ashrrev_i32_e32 v113, 31, v112
	v_lshl_add_u64 v[112:113], v[112:113], 2, s[40:41]
	global_load_dword v114, v[112:113], off
	v_mul_hi_i32 v115, v119, s79
	v_lshrrev_b32_e32 v117, 31, v115
	v_ashrrev_i32_e32 v115, 11, v115
	v_add_u32_e32 v115, v115, v117
	v_mul_i32_i24_e32 v115, 0x2100, v115
	v_sub_u32_e32 v122, v119, v115
	v_cmp_lt_i32_e64 s[18:19], s80, v122
	v_add_u32_e32 v115, 0xffffff00, v122
	v_and_b32_e32 v117, 31, v122
	v_lshrrev_b32_e32 v118, 6, v115
	s_and_b64 s[0:1], vcc, s[18:19]
	s_waitcnt vmcnt(0)
	v_mul_f32_e32 v114, 0x3dd105ec, v114
	v_mul_f32_e32 v124, 0x3fb8aa3b, v114
	v_mov_b32_e32 v211, v124
	v_pk_mul_f32 v[114:115], v[110:111], v[124:125] op_sel_hi:[1,0]
	v_pk_mul_f32 v[110:111], v[108:109], v[124:125] op_sel_hi:[1,0]
	s_and_saveexec_b64 s[64:65], s[0:1]
	s_cbranch_execz .LBB0_2543
	v_cmp_gt_u32_e64 s[0:1], 16, v179
	s_nop 1
	v_cndmask_b32_e64 v108, v117, v118, s[0:1]
	v_lshlrev_b32_e32 v123, 3, v108
	v_and_or_b32 v108, v180, 7, v123
	v_lshlrev_b32_e32 v108, 3, v108
	global_load_dwordx2 v[108:109], v108, s[42:43]
	v_and_or_b32 v123, v180, 6, v123
	v_lshlrev_b32_e32 v123, 3, v123
	global_load_dwordx2 v[200:201], v123, s[42:43] offset:8
	s_waitcnt vmcnt(0)
	v_pk_mul_f32 v[124:125], v[110:111], v[108:109] op_sel:[1,1] op_sel_hi:[0,1]
	v_pk_mul_f32 v[142:143], v[110:111], v[108:109]
	v_pk_fma_f32 v[110:111], v[110:111], v[108:109], v[124:125] op_sel_hi:[1,0,1]
	v_mul_f32_e32 v110, v115, v201
	v_pk_fma_f32 v[158:159], v[114:115], v[200:201], v[110:111] op_sel_hi:[1,1,0] neg_lo:[0,0,1] neg_hi:[0,0,1]
	v_mul_f32_e32 v110, v114, v201
	v_pk_fma_f32 v[108:109], v[114:115], v[200:201], v[110:111] op_sel:[1,0,0] op_sel_hi:[0,1,0]
	v_sub_f32_e32 v110, v142, v124
	v_mov_b32_e32 v114, v158
	v_mov_b32_e32 v115, v108
.LBB0_2543:
	s_or_b64 exec, exec, s[64:65]
	v_mov_b64_e32 v[108:109], s[94:95]
	v_mad_i64_i32 v[108:109], s[0:1], v119, s81, v[108:109]
	v_lshl_add_u64 v[108:109], v[140:141], 1, v[108:109]
	v_cvt_pk_bf16_f32 v110, v110, v111
	v_cvt_pk_bf16_f32 v111, v114, v115
	global_store_dwordx2 v[108:109], v[110:111], off
	v_lshlrev_b32_e32 v110, 3, v122
	v_and_b32_e32 v110, 0x1f8, v110
	s_and_b64 s[4:5], s[12:13], s[18:19]
	v_mov_b32_e32 v114, v211
	v_pk_mul_f32 v[106:107], v[106:107], v[114:115] op_sel_hi:[1,0]
	v_pk_mul_f32 v[104:105], v[104:105], v[114:115] op_sel_hi:[1,0]
	s_and_saveexec_b64 s[0:1], s[4:5]
	s_cbranch_execz .LBB0_2545
	v_and_or_b32 v111, v126, 7, v110
	v_lshlrev_b32_e32 v111, 3, v111
	global_load_dwordx2 v[114:115], v111, s[42:43]
	v_add_u32_e32 v111, 1, v126
	v_and_or_b32 v111, v111, 7, v110
	v_lshlrev_b32_e32 v111, 3, v111
	global_load_dwordx2 v[200:201], v111, s[42:43]
	s_waitcnt vmcnt(0)
	v_pk_mul_f32 v[122:123], v[104:105], v[114:115] op_sel:[1,1] op_sel_hi:[0,1]
	v_pk_mul_f32 v[124:125], v[104:105], v[114:115]
	v_pk_fma_f32 v[104:105], v[104:105], v[114:115], v[122:123] op_sel_hi:[1,0,1]
	v_mul_f32_e32 v104, v107, v201
	v_pk_fma_f32 v[142:143], v[106:107], v[200:201], v[104:105] op_sel_hi:[1,1,0] neg_lo:[0,0,1] neg_hi:[0,0,1]
	v_mul_f32_e32 v104, v106, v201
	v_pk_fma_f32 v[114:115], v[106:107], v[200:201], v[104:105] op_sel:[1,0,0] op_sel_hi:[0,1,0]
	v_sub_f32_e32 v104, v124, v122
	v_mov_b32_e32 v106, v142
	v_mov_b32_e32 v107, v114
.LBB0_2545:
	s_or_b64 exec, exec, s[0:1]
	v_cvt_pk_bf16_f32 v104, v104, v105
	v_cvt_pk_bf16_f32 v105, v106, v107
	global_store_dwordx2 v[108:109], v[104:105], off offset:32
	s_and_b64 s[0:1], s[14:15], s[18:19]
	v_mov_b32_e32 v104, v211
	v_pk_mul_f32 v[102:103], v[102:103], v[104:105] op_sel_hi:[1,0]
	v_pk_mul_f32 v[100:101], v[100:101], v[104:105] op_sel_hi:[1,0]
	s_and_saveexec_b64 s[64:65], s[0:1]
	s_cbranch_execz .LBB0_2547
	v_cmp_gt_u32_e64 s[0:1], 16, v120
	v_add_u32_e32 v107, 1, v121
	s_nop 0
	v_cndmask_b32_e64 v104, v117, v118, s[0:1]
	v_lshlrev_b32_e32 v106, 3, v104
	v_and_or_b32 v104, v121, 7, v106
	v_lshlrev_b32_e32 v104, 3, v104
	global_load_dwordx2 v[104:105], v104, s[42:43]
	v_and_or_b32 v106, v107, 7, v106
	v_lshlrev_b32_e32 v111, 3, v106
	global_load_dwordx2 v[200:201], v111, s[42:43]
	s_waitcnt vmcnt(0)
	v_pk_mul_f32 v[106:107], v[100:101], v[104:105] op_sel:[1,1] op_sel_hi:[0,1]
	v_pk_mul_f32 v[114:115], v[100:101], v[104:105]
	v_pk_fma_f32 v[100:101], v[100:101], v[104:105], v[106:107] op_sel_hi:[1,0,1]
	v_mul_f32_e32 v100, v103, v201
	v_pk_fma_f32 v[118:119], v[102:103], v[200:201], v[100:101] op_sel_hi:[1,1,0] neg_lo:[0,0,1] neg_hi:[0,0,1]
	v_mul_f32_e32 v100, v102, v201
	v_pk_fma_f32 v[104:105], v[102:103], v[200:201], v[100:101] op_sel:[1,0,0] op_sel_hi:[0,1,0]
	v_sub_f32_e32 v100, v114, v106
	v_mov_b32_e32 v102, v118
	v_mov_b32_e32 v103, v104
.LBB0_2547:
	s_or_b64 exec, exec, s[64:65]
	v_cvt_pk_bf16_f32 v100, v100, v101
	v_cvt_pk_bf16_f32 v101, v102, v103
	global_store_dwordx2 v[108:109], v[100:101], off offset:256
	s_and_b64 s[4:5], s[16:17], s[18:19]
	v_mov_b32_e32 v100, v211
	v_pk_mul_f32 v[98:99], v[98:99], v[100:101] op_sel_hi:[1,0]
	v_pk_mul_f32 v[96:97], v[96:97], v[100:101] op_sel_hi:[1,0]
	s_and_saveexec_b64 s[0:1], s[4:5]
	s_cbranch_execz .LBB0_2549
	v_and_or_b32 v100, v116, 7, v110
	v_lshlrev_b32_e32 v100, 3, v100
	global_load_dwordx2 v[100:101], v100, s[42:43]
	v_add_u32_e32 v102, 1, v116
	v_and_or_b32 v102, v102, 7, v110
	v_lshlrev_b32_e32 v106, 3, v102
	global_load_dwordx2 v[200:201], v106, s[42:43]
	s_waitcnt vmcnt(0)
	v_pk_mul_f32 v[102:103], v[96:97], v[100:101] op_sel:[1,1] op_sel_hi:[0,1]
	v_pk_mul_f32 v[104:105], v[96:97], v[100:101]
	v_pk_fma_f32 v[96:97], v[96:97], v[100:101], v[102:103] op_sel_hi:[1,0,1]
	v_mul_f32_e32 v96, v99, v201
	v_pk_fma_f32 v[106:107], v[98:99], v[200:201], v[96:97] op_sel_hi:[1,1,0] neg_lo:[0,0,1] neg_hi:[0,0,1]
	v_mul_f32_e32 v96, v98, v201
	v_pk_fma_f32 v[100:101], v[98:99], v[200:201], v[96:97] op_sel:[1,0,0] op_sel_hi:[0,1,0]
	v_sub_f32_e32 v96, v104, v102
	v_mov_b32_e32 v98, v106
	v_mov_b32_e32 v99, v100
.LBB0_2549:
	s_or_b64 exec, exec, s[0:1]
	v_cvt_pk_bf16_f32 v96, v96, v97
	v_cvt_pk_bf16_f32 v97, v98, v99
	v_or_b32_e32 v102, 32, v178
	global_store_dwordx2 v[108:109], v[96:97], off offset:288
	v_lshlrev_b32_e32 v96, 1, v102
	v_ashrrev_i32_e32 v97, 31, v96
	v_lshl_add_u64 v[96:97], v[96:97], 2, s[40:41]
	global_load_dword v98, v[96:97], off
	v_mul_hi_i32 v99, v102, s79
	v_lshrrev_b32_e32 v100, 31, v99
	v_ashrrev_i32_e32 v99, 11, v99
	v_add_u32_e32 v99, v99, v100
	v_mul_i32_i24_e32 v99, 0x2100, v99
	v_sub_u32_e32 v103, v102, v99
	v_cmp_lt_i32_e64 s[18:19], s80, v103
	v_add_u32_e32 v99, 0xffffff00, v103
	v_and_b32_e32 v100, 47, v103
	v_lshrrev_b32_e32 v101, 6, v99
	s_and_b64 s[0:1], vcc, s[18:19]
	s_waitcnt vmcnt(0)
	v_mul_f32_e32 v98, 0x3dd105ec, v98
	v_mul_f32_e32 v104, 0x3fb8aa3b, v98
	v_mov_b32_e32 v212, v104
	v_pk_mul_f32 v[98:99], v[94:95], v[104:105] op_sel_hi:[1,0]
	v_pk_mul_f32 v[94:95], v[92:93], v[104:105] op_sel_hi:[1,0]
	s_and_saveexec_b64 s[64:65], s[0:1]
	s_cbranch_execz .LBB0_2551
	v_cmp_gt_u32_e64 s[0:1], 16, v179
	s_nop 1
	v_cndmask_b32_e64 v92, v100, v101, s[0:1]
	v_lshlrev_b32_e32 v104, 3, v92
	v_and_or_b32 v92, v180, 7, v104
	v_lshlrev_b32_e32 v92, 3, v92
	global_load_dwordx2 v[92:93], v92, s[42:43]
	v_and_or_b32 v104, v180, 6, v104
	v_lshlrev_b32_e32 v108, 3, v104
	global_load_dwordx2 v[200:201], v108, s[42:43] offset:8
	s_waitcnt vmcnt(0)
	v_pk_mul_f32 v[104:105], v[94:95], v[92:93] op_sel:[1,1] op_sel_hi:[0,1]
	v_pk_mul_f32 v[106:107], v[94:95], v[92:93]
	v_pk_fma_f32 v[94:95], v[94:95], v[92:93], v[104:105] op_sel_hi:[1,0,1]
	v_mul_f32_e32 v94, v99, v201
	v_pk_fma_f32 v[108:109], v[98:99], v[200:201], v[94:95] op_sel_hi:[1,1,0] neg_lo:[0,0,1] neg_hi:[0,0,1]
	v_mul_f32_e32 v94, v98, v201
	v_pk_fma_f32 v[92:93], v[98:99], v[200:201], v[94:95] op_sel:[1,0,0] op_sel_hi:[0,1,0]
	v_sub_f32_e32 v94, v106, v104
	v_mov_b32_e32 v98, v108
	v_mov_b32_e32 v99, v92
.LBB0_2551:
	s_or_b64 exec, exec, s[64:65]
	v_mov_b64_e32 v[92:93], s[94:95]
	v_mad_i64_i32 v[92:93], s[0:1], v102, s81, v[92:93]
	v_lshl_add_u64 v[92:93], v[140:141], 1, v[92:93]
	v_cvt_pk_bf16_f32 v94, v94, v95
	v_cvt_pk_bf16_f32 v95, v98, v99
	global_store_dwordx2 v[92:93], v[94:95], off
	v_lshlrev_b32_e32 v94, 3, v103
	v_and_b32_e32 v94, 0x1f8, v94
	s_and_b64 s[4:5], s[12:13], s[18:19]
	v_mov_b32_e32 v98, v212
	v_pk_mul_f32 v[90:91], v[90:91], v[98:99] op_sel_hi:[1,0]
	v_pk_mul_f32 v[88:89], v[88:89], v[98:99] op_sel_hi:[1,0]
	s_and_saveexec_b64 s[0:1], s[4:5]
	s_cbranch_execz .LBB0_2553
	v_and_or_b32 v95, v126, 7, v94
	v_lshlrev_b32_e32 v95, 3, v95
	global_load_dwordx2 v[98:99], v95, s[42:43]
	v_add_u32_e32 v95, 1, v126
	v_and_or_b32 v95, v95, 7, v94
	v_lshlrev_b32_e32 v95, 3, v95
	global_load_dwordx2 v[200:201], v95, s[42:43]
	s_waitcnt vmcnt(0)
	v_pk_mul_f32 v[102:103], v[88:89], v[98:99] op_sel:[1,1] op_sel_hi:[0,1]
	v_pk_mul_f32 v[104:105], v[88:89], v[98:99]
	v_pk_fma_f32 v[88:89], v[88:89], v[98:99], v[102:103] op_sel_hi:[1,0,1]
	v_mul_f32_e32 v88, v91, v201
	v_pk_fma_f32 v[106:107], v[90:91], v[200:201], v[88:89] op_sel_hi:[1,1,0] neg_lo:[0,0,1] neg_hi:[0,0,1]
	v_mul_f32_e32 v88, v90, v201
	v_pk_fma_f32 v[98:99], v[90:91], v[200:201], v[88:89] op_sel:[1,0,0] op_sel_hi:[0,1,0]
	v_sub_f32_e32 v88, v104, v102
	v_mov_b32_e32 v90, v106
	v_mov_b32_e32 v91, v98
.LBB0_2553:
	s_or_b64 exec, exec, s[0:1]
	v_cvt_pk_bf16_f32 v88, v88, v89
	v_cvt_pk_bf16_f32 v89, v90, v91
	global_store_dwordx2 v[92:93], v[88:89], off offset:32
	s_and_b64 s[0:1], s[14:15], s[18:19]
	v_mov_b32_e32 v88, v212
	v_pk_mul_f32 v[86:87], v[86:87], v[88:89] op_sel_hi:[1,0]
	v_pk_mul_f32 v[84:85], v[84:85], v[88:89] op_sel_hi:[1,0]
	s_and_saveexec_b64 s[64:65], s[0:1]
	s_cbranch_execz .LBB0_2555
	v_cmp_gt_u32_e64 s[0:1], 16, v120
	v_add_u32_e32 v91, 1, v121
	s_nop 0
	v_cndmask_b32_e64 v88, v100, v101, s[0:1]
	v_lshlrev_b32_e32 v90, 3, v88
	v_and_or_b32 v88, v121, 7, v90
	v_lshlrev_b32_e32 v88, 3, v88
	global_load_dwordx2 v[88:89], v88, s[42:43]
	v_and_or_b32 v90, v91, 7, v90
	v_lshlrev_b32_e32 v95, 3, v90
	global_load_dwordx2 v[200:201], v95, s[42:43]
	s_waitcnt vmcnt(0)
	v_pk_mul_f32 v[90:91], v[84:85], v[88:89] op_sel:[1,1] op_sel_hi:[0,1]
	v_pk_mul_f32 v[98:99], v[84:85], v[88:89]
	v_pk_fma_f32 v[84:85], v[84:85], v[88:89], v[90:91] op_sel_hi:[1,0,1]
	v_mul_f32_e32 v84, v87, v201
	v_pk_fma_f32 v[100:101], v[86:87], v[200:201], v[84:85] op_sel_hi:[1,1,0] neg_lo:[0,0,1] neg_hi:[0,0,1]
	v_mul_f32_e32 v84, v86, v201
	v_pk_fma_f32 v[88:89], v[86:87], v[200:201], v[84:85] op_sel:[1,0,0] op_sel_hi:[0,1,0]
	v_sub_f32_e32 v84, v98, v90
	v_mov_b32_e32 v86, v100
	v_mov_b32_e32 v87, v88
.LBB0_2555:
	s_or_b64 exec, exec, s[64:65]
	v_cvt_pk_bf16_f32 v84, v84, v85
	v_cvt_pk_bf16_f32 v85, v86, v87
	global_store_dwordx2 v[92:93], v[84:85], off offset:256
	s_and_b64 s[4:5], s[16:17], s[18:19]
	v_mov_b32_e32 v84, v212
	v_pk_mul_f32 v[82:83], v[82:83], v[84:85] op_sel_hi:[1,0]
	v_pk_mul_f32 v[80:81], v[80:81], v[84:85] op_sel_hi:[1,0]
	s_and_saveexec_b64 s[0:1], s[4:5]
	s_cbranch_execz .LBB0_2557
	v_and_or_b32 v84, v116, 7, v94
	v_lshlrev_b32_e32 v84, 3, v84
	global_load_dwordx2 v[84:85], v84, s[42:43]
	v_add_u32_e32 v86, 1, v116
	v_and_or_b32 v86, v86, 7, v94
	v_lshlrev_b32_e32 v90, 3, v86
	global_load_dwordx2 v[200:201], v90, s[42:43]
	s_waitcnt vmcnt(0)
	v_pk_mul_f32 v[86:87], v[80:81], v[84:85] op_sel:[1,1] op_sel_hi:[0,1]
	v_pk_mul_f32 v[88:89], v[80:81], v[84:85]
	v_pk_fma_f32 v[80:81], v[80:81], v[84:85], v[86:87] op_sel_hi:[1,0,1]
	v_mul_f32_e32 v80, v83, v201
	v_pk_fma_f32 v[90:91], v[82:83], v[200:201], v[80:81] op_sel_hi:[1,1,0] neg_lo:[0,0,1] neg_hi:[0,0,1]
	v_mul_f32_e32 v80, v82, v201
	v_pk_fma_f32 v[84:85], v[82:83], v[200:201], v[80:81] op_sel:[1,0,0] op_sel_hi:[0,1,0]
	v_sub_f32_e32 v80, v88, v86
	v_mov_b32_e32 v82, v90
	v_mov_b32_e32 v83, v84
.LBB0_2557:
	s_or_b64 exec, exec, s[0:1]
	v_cvt_pk_bf16_f32 v80, v80, v81
	v_cvt_pk_bf16_f32 v81, v82, v83
	v_or_b32_e32 v86, 48, v178
	global_store_dwordx2 v[92:93], v[80:81], off offset:288
	v_lshlrev_b32_e32 v80, 1, v86
	v_ashrrev_i32_e32 v81, 31, v80
	v_lshl_add_u64 v[80:81], v[80:81], 2, s[40:41]
	global_load_dword v82, v[80:81], off
	v_mul_hi_i32 v83, v86, s79
	v_lshrrev_b32_e32 v84, 31, v83
	v_ashrrev_i32_e32 v83, 11, v83
	v_add_u32_e32 v83, v83, v84
	v_mul_i32_i24_e32 v83, 0x2100, v83
	v_sub_u32_e32 v87, v86, v83
	v_cmp_lt_i32_e64 s[18:19], s80, v87
	v_add_u32_e32 v83, 0xffffff00, v87
	v_and_b32_e32 v84, 63, v87
	v_lshrrev_b32_e32 v85, 6, v83
	s_and_b64 s[0:1], vcc, s[18:19]
	s_waitcnt vmcnt(0)
	v_mul_f32_e32 v82, 0x3dd105ec, v82
	v_mul_f32_e32 v88, 0x3fb8aa3b, v82
	v_mov_b32_e32 v213, v88
	v_pk_mul_f32 v[82:83], v[78:79], v[88:89] op_sel_hi:[1,0]
	v_pk_mul_f32 v[78:79], v[76:77], v[88:89] op_sel_hi:[1,0]
	s_and_saveexec_b64 s[64:65], s[0:1]
	s_cbranch_execz .LBB0_2559
	v_cmp_gt_u32_e64 s[0:1], 16, v179
	s_nop 1
	v_cndmask_b32_e64 v76, v84, v85, s[0:1]
	v_lshlrev_b32_e32 v88, 3, v76
	v_and_or_b32 v76, v180, 7, v88
	v_lshlrev_b32_e32 v76, 3, v76
	global_load_dwordx2 v[76:77], v76, s[42:43]
	v_and_or_b32 v88, v180, 6, v88
	v_lshlrev_b32_e32 v92, 3, v88
	global_load_dwordx2 v[200:201], v92, s[42:43] offset:8
	s_waitcnt vmcnt(0)
	v_pk_mul_f32 v[88:89], v[78:79], v[76:77] op_sel:[1,1] op_sel_hi:[0,1]
	v_pk_mul_f32 v[90:91], v[78:79], v[76:77]
	v_pk_fma_f32 v[78:79], v[78:79], v[76:77], v[88:89] op_sel_hi:[1,0,1]
	v_mul_f32_e32 v78, v83, v201
	v_pk_fma_f32 v[92:93], v[82:83], v[200:201], v[78:79] op_sel_hi:[1,1,0] neg_lo:[0,0,1] neg_hi:[0,0,1]
	v_mul_f32_e32 v78, v82, v201
	v_pk_fma_f32 v[76:77], v[82:83], v[200:201], v[78:79] op_sel:[1,0,0] op_sel_hi:[0,1,0]
	v_sub_f32_e32 v78, v90, v88
	v_mov_b32_e32 v82, v92
	v_mov_b32_e32 v83, v76
.LBB0_2559:
	s_or_b64 exec, exec, s[64:65]
	v_mov_b64_e32 v[76:77], s[94:95]
	v_mad_i64_i32 v[76:77], s[0:1], v86, s81, v[76:77]
	v_lshl_add_u64 v[76:77], v[140:141], 1, v[76:77]
	v_cvt_pk_bf16_f32 v78, v78, v79
	v_cvt_pk_bf16_f32 v79, v82, v83
	global_store_dwordx2 v[76:77], v[78:79], off
	v_lshlrev_b32_e32 v78, 3, v87
	v_and_b32_e32 v78, 0x1f8, v78
	s_and_b64 s[4:5], s[12:13], s[18:19]
	v_mov_b32_e32 v82, v213
	v_pk_mul_f32 v[74:75], v[74:75], v[82:83] op_sel_hi:[1,0]
	v_pk_mul_f32 v[72:73], v[72:73], v[82:83] op_sel_hi:[1,0]
	s_and_saveexec_b64 s[0:1], s[4:5]
	s_cbranch_execz .LBB0_2561
	v_and_or_b32 v79, v126, 7, v78
	v_lshlrev_b32_e32 v79, 3, v79
	global_load_dwordx2 v[82:83], v79, s[42:43]
	v_add_u32_e32 v79, 1, v126
	v_and_or_b32 v79, v79, 7, v78
	v_lshlrev_b32_e32 v79, 3, v79
	global_load_dwordx2 v[200:201], v79, s[42:43]
	s_waitcnt vmcnt(0)
	v_pk_mul_f32 v[86:87], v[72:73], v[82:83] op_sel:[1,1] op_sel_hi:[0,1]
	v_pk_mul_f32 v[88:89], v[72:73], v[82:83]
	v_pk_fma_f32 v[72:73], v[72:73], v[82:83], v[86:87] op_sel_hi:[1,0,1]
	v_mul_f32_e32 v72, v75, v201
	v_pk_fma_f32 v[90:91], v[74:75], v[200:201], v[72:73] op_sel_hi:[1,1,0] neg_lo:[0,0,1] neg_hi:[0,0,1]
	v_mul_f32_e32 v72, v74, v201
	v_pk_fma_f32 v[82:83], v[74:75], v[200:201], v[72:73] op_sel:[1,0,0] op_sel_hi:[0,1,0]
	v_sub_f32_e32 v72, v88, v86
	v_mov_b32_e32 v74, v90
	v_mov_b32_e32 v75, v82
.LBB0_2561:
	s_or_b64 exec, exec, s[0:1]
	v_cvt_pk_bf16_f32 v72, v72, v73
	v_cvt_pk_bf16_f32 v73, v74, v75
	global_store_dwordx2 v[76:77], v[72:73], off offset:32
	s_and_b64 s[0:1], s[14:15], s[18:19]
	v_mov_b32_e32 v72, v213
	v_pk_mul_f32 v[70:71], v[70:71], v[72:73] op_sel_hi:[1,0]
	v_pk_mul_f32 v[68:69], v[68:69], v[72:73] op_sel_hi:[1,0]
	s_and_saveexec_b64 s[64:65], s[0:1]
	s_cbranch_execz .LBB0_2563
	v_cmp_gt_u32_e64 s[0:1], 16, v120
	v_add_u32_e32 v75, 1, v121
	s_nop 0
	v_cndmask_b32_e64 v72, v84, v85, s[0:1]
	v_lshlrev_b32_e32 v74, 3, v72
	v_and_or_b32 v72, v121, 7, v74
	v_lshlrev_b32_e32 v72, 3, v72
	global_load_dwordx2 v[72:73], v72, s[42:43]
	v_and_or_b32 v74, v75, 7, v74
	v_lshlrev_b32_e32 v79, 3, v74
	global_load_dwordx2 v[200:201], v79, s[42:43]
	s_waitcnt vmcnt(0)
	v_pk_mul_f32 v[74:75], v[68:69], v[72:73] op_sel:[1,1] op_sel_hi:[0,1]
	v_pk_mul_f32 v[82:83], v[68:69], v[72:73]
	v_pk_fma_f32 v[68:69], v[68:69], v[72:73], v[74:75] op_sel_hi:[1,0,1]
	v_mul_f32_e32 v68, v71, v201
	v_pk_fma_f32 v[84:85], v[70:71], v[200:201], v[68:69] op_sel_hi:[1,1,0] neg_lo:[0,0,1] neg_hi:[0,0,1]
	v_mul_f32_e32 v68, v70, v201
	v_pk_fma_f32 v[72:73], v[70:71], v[200:201], v[68:69] op_sel:[1,0,0] op_sel_hi:[0,1,0]
	v_sub_f32_e32 v68, v82, v74
	v_mov_b32_e32 v70, v84
	v_mov_b32_e32 v71, v72
.LBB0_2563:
	s_or_b64 exec, exec, s[64:65]
	v_cvt_pk_bf16_f32 v68, v68, v69
	v_cvt_pk_bf16_f32 v69, v70, v71
	global_store_dwordx2 v[76:77], v[68:69], off offset:256
	s_and_b64 s[4:5], s[16:17], s[18:19]
	v_mov_b32_e32 v68, v213
	v_pk_mul_f32 v[66:67], v[66:67], v[68:69] op_sel_hi:[1,0]
	v_pk_mul_f32 v[64:65], v[64:65], v[68:69] op_sel_hi:[1,0]
	s_and_saveexec_b64 s[0:1], s[4:5]
	s_cbranch_execz .LBB0_2565
	v_and_or_b32 v68, v116, 7, v78
	v_lshlrev_b32_e32 v68, 3, v68
	global_load_dwordx2 v[68:69], v68, s[42:43]
	v_add_u32_e32 v70, 1, v116
	v_and_or_b32 v70, v70, 7, v78
	v_lshlrev_b32_e32 v74, 3, v70
	global_load_dwordx2 v[200:201], v74, s[42:43]
	s_waitcnt vmcnt(0)
	v_pk_mul_f32 v[70:71], v[64:65], v[68:69] op_sel:[1,1] op_sel_hi:[0,1]
	v_pk_mul_f32 v[72:73], v[64:65], v[68:69]
	v_pk_fma_f32 v[64:65], v[64:65], v[68:69], v[70:71] op_sel_hi:[1,0,1]
	v_mul_f32_e32 v64, v67, v201
	v_pk_fma_f32 v[74:75], v[66:67], v[200:201], v[64:65] op_sel_hi:[1,1,0] neg_lo:[0,0,1] neg_hi:[0,0,1]
	v_mul_f32_e32 v64, v66, v201
	v_pk_fma_f32 v[68:69], v[66:67], v[200:201], v[64:65] op_sel:[1,0,0] op_sel_hi:[0,1,0]
	v_sub_f32_e32 v64, v72, v70
	v_mov_b32_e32 v66, v74
	v_mov_b32_e32 v67, v68
.LBB0_2565:
	s_or_b64 exec, exec, s[0:1]
	v_cvt_pk_bf16_f32 v64, v64, v65
	v_cvt_pk_bf16_f32 v65, v66, v67
	v_add_u32_e32 v70, 0x80, v178
	global_store_dwordx2 v[76:77], v[64:65], off offset:288
	v_lshlrev_b32_e32 v64, 1, v70
	v_ashrrev_i32_e32 v65, 31, v64
	v_lshl_add_u64 v[64:65], v[64:65], 2, s[40:41]
	global_load_dword v66, v[64:65], off
	v_mul_hi_i32 v67, v70, s79
	v_lshrrev_b32_e32 v68, 31, v67
	v_ashrrev_i32_e32 v67, 11, v67
	v_add_u32_e32 v67, v67, v68
	v_mul_i32_i24_e32 v67, 0x2100, v67
	v_sub_u32_e32 v71, v70, v67
	v_cmp_lt_i32_e64 s[18:19], s80, v71
	v_add_u32_e32 v67, 0xffffff00, v71
	v_and_b32_e32 v68, 15, v71
	v_lshrrev_b32_e32 v69, 6, v67
	s_and_b64 s[0:1], vcc, s[18:19]
	s_waitcnt vmcnt(0)
	v_mul_f32_e32 v66, 0x3dd105ec, v66
	v_mul_f32_e32 v72, 0x3fb8aa3b, v66
	v_mov_b32_e32 v214, v72
	v_pk_mul_f32 v[66:67], v[62:63], v[72:73] op_sel_hi:[1,0]
	v_pk_mul_f32 v[62:63], v[60:61], v[72:73] op_sel_hi:[1,0]
	s_and_saveexec_b64 s[64:65], s[0:1]
	s_cbranch_execz .LBB0_2567
	v_cmp_gt_u32_e64 s[0:1], 16, v179
	s_nop 1
	v_cndmask_b32_e64 v60, v68, v69, s[0:1]
	v_lshlrev_b32_e32 v72, 3, v60
	v_and_or_b32 v60, v180, 7, v72
	v_lshlrev_b32_e32 v60, 3, v60
	global_load_dwordx2 v[60:61], v60, s[42:43]
	v_and_or_b32 v72, v180, 6, v72
	v_lshlrev_b32_e32 v76, 3, v72
	global_load_dwordx2 v[200:201], v76, s[42:43] offset:8
	s_waitcnt vmcnt(0)
	v_pk_mul_f32 v[72:73], v[62:63], v[60:61] op_sel:[1,1] op_sel_hi:[0,1]
	v_pk_mul_f32 v[74:75], v[62:63], v[60:61]
	v_pk_fma_f32 v[62:63], v[62:63], v[60:61], v[72:73] op_sel_hi:[1,0,1]
	v_mul_f32_e32 v62, v67, v201
	v_pk_fma_f32 v[76:77], v[66:67], v[200:201], v[62:63] op_sel_hi:[1,1,0] neg_lo:[0,0,1] neg_hi:[0,0,1]
	v_mul_f32_e32 v62, v66, v201
	v_pk_fma_f32 v[60:61], v[66:67], v[200:201], v[62:63] op_sel:[1,0,0] op_sel_hi:[0,1,0]
	v_sub_f32_e32 v62, v74, v72
	v_mov_b32_e32 v66, v76
	v_mov_b32_e32 v67, v60
.LBB0_2567:
	s_or_b64 exec, exec, s[64:65]
	v_mov_b64_e32 v[60:61], s[94:95]
	v_mad_i64_i32 v[60:61], s[0:1], v70, s81, v[60:61]
	v_lshl_add_u64 v[60:61], v[140:141], 1, v[60:61]
	v_cvt_pk_bf16_f32 v62, v62, v63
	v_cvt_pk_bf16_f32 v63, v66, v67
	global_store_dwordx2 v[60:61], v[62:63], off
	v_lshlrev_b32_e32 v62, 3, v71
	v_and_b32_e32 v62, 0x1f8, v62
	s_and_b64 s[4:5], s[12:13], s[18:19]
	v_mov_b32_e32 v66, v214
	v_pk_mul_f32 v[58:59], v[58:59], v[66:67] op_sel_hi:[1,0]
	v_pk_mul_f32 v[56:57], v[56:57], v[66:67] op_sel_hi:[1,0]
	s_and_saveexec_b64 s[0:1], s[4:5]
	s_cbranch_execz .LBB0_2569
	v_and_or_b32 v63, v126, 7, v62
	v_lshlrev_b32_e32 v63, 3, v63
	global_load_dwordx2 v[66:67], v63, s[42:43]
	v_add_u32_e32 v63, 1, v126
	v_and_or_b32 v63, v63, 7, v62
	v_lshlrev_b32_e32 v63, 3, v63
	global_load_dwordx2 v[200:201], v63, s[42:43]
	s_waitcnt vmcnt(0)
	v_pk_mul_f32 v[70:71], v[56:57], v[66:67] op_sel:[1,1] op_sel_hi:[0,1]
	v_pk_mul_f32 v[72:73], v[56:57], v[66:67]
	v_pk_fma_f32 v[56:57], v[56:57], v[66:67], v[70:71] op_sel_hi:[1,0,1]
	v_mul_f32_e32 v56, v59, v201
	v_pk_fma_f32 v[74:75], v[58:59], v[200:201], v[56:57] op_sel_hi:[1,1,0] neg_lo:[0,0,1] neg_hi:[0,0,1]
	v_mul_f32_e32 v56, v58, v201
	v_pk_fma_f32 v[66:67], v[58:59], v[200:201], v[56:57] op_sel:[1,0,0] op_sel_hi:[0,1,0]
	v_sub_f32_e32 v56, v72, v70
	v_mov_b32_e32 v58, v74
	v_mov_b32_e32 v59, v66
.LBB0_2569:
	s_or_b64 exec, exec, s[0:1]
	v_cvt_pk_bf16_f32 v56, v56, v57
	v_cvt_pk_bf16_f32 v57, v58, v59
	global_store_dwordx2 v[60:61], v[56:57], off offset:32
	s_and_b64 s[0:1], s[14:15], s[18:19]
	v_mov_b32_e32 v56, v214
	v_pk_mul_f32 v[54:55], v[54:55], v[56:57] op_sel_hi:[1,0]
	v_pk_mul_f32 v[52:53], v[52:53], v[56:57] op_sel_hi:[1,0]
	s_and_saveexec_b64 s[64:65], s[0:1]
	s_cbranch_execz .LBB0_2571
	v_cmp_gt_u32_e64 s[0:1], 16, v120
	v_add_u32_e32 v59, 1, v121
	s_nop 0
	v_cndmask_b32_e64 v56, v68, v69, s[0:1]
	v_lshlrev_b32_e32 v58, 3, v56
	v_and_or_b32 v56, v121, 7, v58
	v_lshlrev_b32_e32 v56, 3, v56
	global_load_dwordx2 v[56:57], v56, s[42:43]
	v_and_or_b32 v58, v59, 7, v58
	v_lshlrev_b32_e32 v63, 3, v58
	global_load_dwordx2 v[200:201], v63, s[42:43]
	s_waitcnt vmcnt(0)
	v_pk_mul_f32 v[58:59], v[52:53], v[56:57] op_sel:[1,1] op_sel_hi:[0,1]
	v_pk_mul_f32 v[66:67], v[52:53], v[56:57]
	v_pk_fma_f32 v[52:53], v[52:53], v[56:57], v[58:59] op_sel_hi:[1,0,1]
	v_mul_f32_e32 v52, v55, v201
	v_pk_fma_f32 v[68:69], v[54:55], v[200:201], v[52:53] op_sel_hi:[1,1,0] neg_lo:[0,0,1] neg_hi:[0,0,1]
	v_mul_f32_e32 v52, v54, v201
	v_pk_fma_f32 v[56:57], v[54:55], v[200:201], v[52:53] op_sel:[1,0,0] op_sel_hi:[0,1,0]
	v_sub_f32_e32 v52, v66, v58
	v_mov_b32_e32 v54, v68
	v_mov_b32_e32 v55, v56
.LBB0_2571:
	s_or_b64 exec, exec, s[64:65]
	v_cvt_pk_bf16_f32 v52, v52, v53
	v_cvt_pk_bf16_f32 v53, v54, v55
	global_store_dwordx2 v[60:61], v[52:53], off offset:256
	s_and_b64 s[4:5], s[16:17], s[18:19]
	v_mov_b32_e32 v52, v214
	v_pk_mul_f32 v[50:51], v[50:51], v[52:53] op_sel_hi:[1,0]
	v_pk_mul_f32 v[48:49], v[48:49], v[52:53] op_sel_hi:[1,0]
	s_and_saveexec_b64 s[0:1], s[4:5]
	s_cbranch_execz .LBB0_2573
	v_and_or_b32 v52, v116, 7, v62
	v_lshlrev_b32_e32 v52, 3, v52
	global_load_dwordx2 v[52:53], v52, s[42:43]
	v_add_u32_e32 v54, 1, v116
	v_and_or_b32 v54, v54, 7, v62
	v_lshlrev_b32_e32 v58, 3, v54
	global_load_dwordx2 v[200:201], v58, s[42:43]
	s_waitcnt vmcnt(0)
	v_pk_mul_f32 v[54:55], v[48:49], v[52:53] op_sel:[1,1] op_sel_hi:[0,1]
	v_pk_mul_f32 v[56:57], v[48:49], v[52:53]
	v_pk_fma_f32 v[48:49], v[48:49], v[52:53], v[54:55] op_sel_hi:[1,0,1]
	v_mul_f32_e32 v48, v51, v201
	v_pk_fma_f32 v[58:59], v[50:51], v[200:201], v[48:49] op_sel_hi:[1,1,0] neg_lo:[0,0,1] neg_hi:[0,0,1]
	v_mul_f32_e32 v48, v50, v201
	v_pk_fma_f32 v[52:53], v[50:51], v[200:201], v[48:49] op_sel:[1,0,0] op_sel_hi:[0,1,0]
	v_sub_f32_e32 v48, v56, v54
	v_mov_b32_e32 v50, v58
	v_mov_b32_e32 v51, v52
.LBB0_2573:
	s_or_b64 exec, exec, s[0:1]
	v_cvt_pk_bf16_f32 v48, v48, v49
	v_cvt_pk_bf16_f32 v49, v50, v51
	v_add_u32_e32 v54, 0x90, v178
	global_store_dwordx2 v[60:61], v[48:49], off offset:288
	v_lshlrev_b32_e32 v48, 1, v54
	v_ashrrev_i32_e32 v49, 31, v48
	v_lshl_add_u64 v[48:49], v[48:49], 2, s[40:41]
	global_load_dword v50, v[48:49], off
	v_mul_hi_i32 v51, v54, s79
	v_lshrrev_b32_e32 v52, 31, v51
	v_ashrrev_i32_e32 v51, 11, v51
	v_add_u32_e32 v51, v51, v52
	v_mul_i32_i24_e32 v51, 0x2100, v51
	v_sub_u32_e32 v55, v54, v51
	v_cmp_lt_i32_e64 s[18:19], s80, v55
	v_add_u32_e32 v51, 0xffffff00, v55
	v_and_b32_e32 v52, 31, v55
	v_lshrrev_b32_e32 v53, 6, v51
	s_and_b64 s[0:1], vcc, s[18:19]
	s_waitcnt vmcnt(0)
	v_mul_f32_e32 v50, 0x3dd105ec, v50
	v_mul_f32_e32 v56, 0x3fb8aa3b, v50
	v_mov_b32_e32 v215, v56
	v_pk_mul_f32 v[50:51], v[46:47], v[56:57] op_sel_hi:[1,0]
	v_pk_mul_f32 v[46:47], v[44:45], v[56:57] op_sel_hi:[1,0]
	s_and_saveexec_b64 s[64:65], s[0:1]
	s_cbranch_execz .LBB0_2575
	v_cmp_gt_u32_e64 s[0:1], 16, v179
	s_nop 1
	v_cndmask_b32_e64 v44, v52, v53, s[0:1]
	v_lshlrev_b32_e32 v56, 3, v44
	v_and_or_b32 v44, v180, 7, v56
	v_lshlrev_b32_e32 v44, 3, v44
	global_load_dwordx2 v[44:45], v44, s[42:43]
	v_and_or_b32 v56, v180, 6, v56
	v_lshlrev_b32_e32 v60, 3, v56
	global_load_dwordx2 v[200:201], v60, s[42:43] offset:8
	s_waitcnt vmcnt(0)
	v_pk_mul_f32 v[56:57], v[46:47], v[44:45] op_sel:[1,1] op_sel_hi:[0,1]
	v_pk_mul_f32 v[58:59], v[46:47], v[44:45]
	v_pk_fma_f32 v[46:47], v[46:47], v[44:45], v[56:57] op_sel_hi:[1,0,1]
	v_mul_f32_e32 v46, v51, v201
	v_pk_fma_f32 v[60:61], v[50:51], v[200:201], v[46:47] op_sel_hi:[1,1,0] neg_lo:[0,0,1] neg_hi:[0,0,1]
	v_mul_f32_e32 v46, v50, v201
	v_pk_fma_f32 v[44:45], v[50:51], v[200:201], v[46:47] op_sel:[1,0,0] op_sel_hi:[0,1,0]
	v_sub_f32_e32 v46, v58, v56
	v_mov_b32_e32 v50, v60
	v_mov_b32_e32 v51, v44
.LBB0_2575:
	s_or_b64 exec, exec, s[64:65]
	v_mov_b64_e32 v[44:45], s[94:95]
	v_mad_i64_i32 v[44:45], s[0:1], v54, s81, v[44:45]
	v_lshl_add_u64 v[44:45], v[140:141], 1, v[44:45]
	v_cvt_pk_bf16_f32 v46, v46, v47
	v_cvt_pk_bf16_f32 v47, v50, v51
	global_store_dwordx2 v[44:45], v[46:47], off
	v_lshlrev_b32_e32 v46, 3, v55
	v_and_b32_e32 v46, 0x1f8, v46
	s_and_b64 s[4:5], s[12:13], s[18:19]
	v_mov_b32_e32 v50, v215
	v_pk_mul_f32 v[42:43], v[42:43], v[50:51] op_sel_hi:[1,0]
	v_pk_mul_f32 v[40:41], v[40:41], v[50:51] op_sel_hi:[1,0]
	s_and_saveexec_b64 s[0:1], s[4:5]
	s_cbranch_execz .LBB0_2577
	v_and_or_b32 v47, v126, 7, v46
	v_lshlrev_b32_e32 v47, 3, v47
	global_load_dwordx2 v[50:51], v47, s[42:43]
	v_add_u32_e32 v47, 1, v126
	v_and_or_b32 v47, v47, 7, v46
	v_lshlrev_b32_e32 v47, 3, v47
	global_load_dwordx2 v[200:201], v47, s[42:43]
	s_waitcnt vmcnt(0)
	v_pk_mul_f32 v[54:55], v[40:41], v[50:51] op_sel:[1,1] op_sel_hi:[0,1]
	v_pk_mul_f32 v[56:57], v[40:41], v[50:51]
	v_pk_fma_f32 v[40:41], v[40:41], v[50:51], v[54:55] op_sel_hi:[1,0,1]
	v_mul_f32_e32 v40, v43, v201
	v_pk_fma_f32 v[58:59], v[42:43], v[200:201], v[40:41] op_sel_hi:[1,1,0] neg_lo:[0,0,1] neg_hi:[0,0,1]
	v_mul_f32_e32 v40, v42, v201
	v_pk_fma_f32 v[50:51], v[42:43], v[200:201], v[40:41] op_sel:[1,0,0] op_sel_hi:[0,1,0]
	v_sub_f32_e32 v40, v56, v54
	v_mov_b32_e32 v42, v58
	v_mov_b32_e32 v43, v50
.LBB0_2577:
	s_or_b64 exec, exec, s[0:1]
	v_cvt_pk_bf16_f32 v40, v40, v41
	v_cvt_pk_bf16_f32 v41, v42, v43
	global_store_dwordx2 v[44:45], v[40:41], off offset:32
	s_and_b64 s[0:1], s[14:15], s[18:19]
	v_mov_b32_e32 v40, v215
	v_pk_mul_f32 v[38:39], v[38:39], v[40:41] op_sel_hi:[1,0]
	v_pk_mul_f32 v[36:37], v[36:37], v[40:41] op_sel_hi:[1,0]
	s_and_saveexec_b64 s[64:65], s[0:1]
	s_cbranch_execz .LBB0_2579
	v_cmp_gt_u32_e64 s[0:1], 16, v120
	v_add_u32_e32 v43, 1, v121
	s_nop 0
	v_cndmask_b32_e64 v40, v52, v53, s[0:1]
	v_lshlrev_b32_e32 v42, 3, v40
	v_and_or_b32 v40, v121, 7, v42
	v_lshlrev_b32_e32 v40, 3, v40
	global_load_dwordx2 v[40:41], v40, s[42:43]
	v_and_or_b32 v42, v43, 7, v42
	v_lshlrev_b32_e32 v47, 3, v42
	global_load_dwordx2 v[200:201], v47, s[42:43]
	s_waitcnt vmcnt(0)
	v_pk_mul_f32 v[42:43], v[36:37], v[40:41] op_sel:[1,1] op_sel_hi:[0,1]
	v_pk_mul_f32 v[50:51], v[36:37], v[40:41]
	v_pk_fma_f32 v[36:37], v[36:37], v[40:41], v[42:43] op_sel_hi:[1,0,1]
	v_mul_f32_e32 v36, v39, v201
	v_pk_fma_f32 v[52:53], v[38:39], v[200:201], v[36:37] op_sel_hi:[1,1,0] neg_lo:[0,0,1] neg_hi:[0,0,1]
	v_mul_f32_e32 v36, v38, v201
	v_pk_fma_f32 v[40:41], v[38:39], v[200:201], v[36:37] op_sel:[1,0,0] op_sel_hi:[0,1,0]
	v_sub_f32_e32 v36, v50, v42
	v_mov_b32_e32 v38, v52
	v_mov_b32_e32 v39, v40
.LBB0_2579:
	s_or_b64 exec, exec, s[64:65]
	v_cvt_pk_bf16_f32 v36, v36, v37
	v_cvt_pk_bf16_f32 v37, v38, v39
	global_store_dwordx2 v[44:45], v[36:37], off offset:256
	s_and_b64 s[4:5], s[16:17], s[18:19]
	v_mov_b32_e32 v36, v215
	v_pk_mul_f32 v[34:35], v[34:35], v[36:37] op_sel_hi:[1,0]
	v_pk_mul_f32 v[32:33], v[32:33], v[36:37] op_sel_hi:[1,0]
	s_and_saveexec_b64 s[0:1], s[4:5]
	s_cbranch_execz .LBB0_2581
	v_and_or_b32 v36, v116, 7, v46
	v_lshlrev_b32_e32 v36, 3, v36
	global_load_dwordx2 v[36:37], v36, s[42:43]
	v_add_u32_e32 v38, 1, v116
	v_and_or_b32 v38, v38, 7, v46
	v_lshlrev_b32_e32 v42, 3, v38
	global_load_dwordx2 v[200:201], v42, s[42:43]
	s_waitcnt vmcnt(0)
	v_pk_mul_f32 v[38:39], v[32:33], v[36:37] op_sel:[1,1] op_sel_hi:[0,1]
	v_pk_mul_f32 v[40:41], v[32:33], v[36:37]
	v_pk_fma_f32 v[32:33], v[32:33], v[36:37], v[38:39] op_sel_hi:[1,0,1]
	v_mul_f32_e32 v32, v35, v201
	v_pk_fma_f32 v[42:43], v[34:35], v[200:201], v[32:33] op_sel_hi:[1,1,0] neg_lo:[0,0,1] neg_hi:[0,0,1]
	v_mul_f32_e32 v32, v34, v201
	v_pk_fma_f32 v[36:37], v[34:35], v[200:201], v[32:33] op_sel:[1,0,0] op_sel_hi:[0,1,0]
	v_sub_f32_e32 v32, v40, v38
	v_mov_b32_e32 v34, v42
	v_mov_b32_e32 v35, v36
.LBB0_2581:
	s_or_b64 exec, exec, s[0:1]
	v_cvt_pk_bf16_f32 v32, v32, v33
	v_cvt_pk_bf16_f32 v33, v34, v35
	v_add_u32_e32 v38, 0xa0, v178
	global_store_dwordx2 v[44:45], v[32:33], off offset:288
	v_lshlrev_b32_e32 v32, 1, v38
	v_ashrrev_i32_e32 v33, 31, v32
	v_lshl_add_u64 v[32:33], v[32:33], 2, s[40:41]
	global_load_dword v34, v[32:33], off
	v_mul_hi_i32 v35, v38, s79
	v_lshrrev_b32_e32 v36, 31, v35
	v_ashrrev_i32_e32 v35, 11, v35
	v_add_u32_e32 v35, v35, v36
	v_mul_i32_i24_e32 v35, 0x2100, v35
	v_sub_u32_e32 v39, v38, v35
	v_cmp_lt_i32_e64 s[18:19], s80, v39
	v_add_u32_e32 v35, 0xffffff00, v39
	v_and_b32_e32 v36, 47, v39
	v_lshrrev_b32_e32 v37, 6, v35
	s_and_b64 s[0:1], vcc, s[18:19]
	s_waitcnt vmcnt(0)
	v_mul_f32_e32 v34, 0x3dd105ec, v34
	v_mul_f32_e32 v40, 0x3fb8aa3b, v34
	v_mov_b32_e32 v216, v40
	v_pk_mul_f32 v[34:35], v[30:31], v[40:41] op_sel_hi:[1,0]
	v_pk_mul_f32 v[30:31], v[28:29], v[40:41] op_sel_hi:[1,0]
	s_and_saveexec_b64 s[64:65], s[0:1]
	s_cbranch_execz .LBB0_2583
	v_cmp_gt_u32_e64 s[0:1], 16, v179
	s_nop 1
	v_cndmask_b32_e64 v28, v36, v37, s[0:1]
	v_lshlrev_b32_e32 v40, 3, v28
	v_and_or_b32 v28, v180, 7, v40
	v_lshlrev_b32_e32 v28, 3, v28
	global_load_dwordx2 v[28:29], v28, s[42:43]
	v_and_or_b32 v40, v180, 6, v40
	v_lshlrev_b32_e32 v44, 3, v40
	global_load_dwordx2 v[200:201], v44, s[42:43] offset:8
	s_waitcnt vmcnt(0)
	v_pk_mul_f32 v[40:41], v[30:31], v[28:29] op_sel:[1,1] op_sel_hi:[0,1]
	v_pk_mul_f32 v[42:43], v[30:31], v[28:29]
	v_pk_fma_f32 v[30:31], v[30:31], v[28:29], v[40:41] op_sel_hi:[1,0,1]
	v_mul_f32_e32 v30, v35, v201
	v_pk_fma_f32 v[44:45], v[34:35], v[200:201], v[30:31] op_sel_hi:[1,1,0] neg_lo:[0,0,1] neg_hi:[0,0,1]
	v_mul_f32_e32 v30, v34, v201
	v_pk_fma_f32 v[28:29], v[34:35], v[200:201], v[30:31] op_sel:[1,0,0] op_sel_hi:[0,1,0]
	v_sub_f32_e32 v30, v42, v40
	v_mov_b32_e32 v34, v44
	v_mov_b32_e32 v35, v28
.LBB0_2583:
	s_or_b64 exec, exec, s[64:65]
	v_mov_b64_e32 v[28:29], s[94:95]
	v_mad_i64_i32 v[28:29], s[0:1], v38, s81, v[28:29]
	v_lshl_add_u64 v[28:29], v[140:141], 1, v[28:29]
	v_cvt_pk_bf16_f32 v30, v30, v31
	v_cvt_pk_bf16_f32 v31, v34, v35
	global_store_dwordx2 v[28:29], v[30:31], off
	v_lshlrev_b32_e32 v30, 3, v39
	v_and_b32_e32 v30, 0x1f8, v30
	s_and_b64 s[4:5], s[12:13], s[18:19]
	v_mov_b32_e32 v34, v216
	v_pk_mul_f32 v[26:27], v[26:27], v[34:35] op_sel_hi:[1,0]
	v_pk_mul_f32 v[24:25], v[24:25], v[34:35] op_sel_hi:[1,0]
	s_and_saveexec_b64 s[0:1], s[4:5]
	s_cbranch_execz .LBB0_2585
	v_and_or_b32 v31, v126, 7, v30
	v_lshlrev_b32_e32 v31, 3, v31
	global_load_dwordx2 v[34:35], v31, s[42:43]
	v_add_u32_e32 v31, 1, v126
	v_and_or_b32 v31, v31, 7, v30
	v_lshlrev_b32_e32 v31, 3, v31
	global_load_dwordx2 v[200:201], v31, s[42:43]
	s_waitcnt vmcnt(0)
	v_pk_mul_f32 v[38:39], v[24:25], v[34:35] op_sel:[1,1] op_sel_hi:[0,1]
	v_pk_mul_f32 v[40:41], v[24:25], v[34:35]
	v_pk_fma_f32 v[24:25], v[24:25], v[34:35], v[38:39] op_sel_hi:[1,0,1]
	v_mul_f32_e32 v24, v27, v201
	v_pk_fma_f32 v[42:43], v[26:27], v[200:201], v[24:25] op_sel_hi:[1,1,0] neg_lo:[0,0,1] neg_hi:[0,0,1]
	v_mul_f32_e32 v24, v26, v201
	v_pk_fma_f32 v[34:35], v[26:27], v[200:201], v[24:25] op_sel:[1,0,0] op_sel_hi:[0,1,0]
	v_sub_f32_e32 v24, v40, v38
	v_mov_b32_e32 v26, v42
	v_mov_b32_e32 v27, v34
.LBB0_2585:
	s_or_b64 exec, exec, s[0:1]
	v_cvt_pk_bf16_f32 v24, v24, v25
	v_cvt_pk_bf16_f32 v25, v26, v27
	global_store_dwordx2 v[28:29], v[24:25], off offset:32
	s_and_b64 s[0:1], s[14:15], s[18:19]
	v_mov_b32_e32 v24, v216
	v_pk_mul_f32 v[22:23], v[22:23], v[24:25] op_sel_hi:[1,0]
	v_pk_mul_f32 v[20:21], v[20:21], v[24:25] op_sel_hi:[1,0]
	s_and_saveexec_b64 s[64:65], s[0:1]
	s_cbranch_execz .LBB0_2587
	v_cmp_gt_u32_e64 s[0:1], 16, v120
	v_add_u32_e32 v27, 1, v121
	s_nop 0
	v_cndmask_b32_e64 v24, v36, v37, s[0:1]
	v_lshlrev_b32_e32 v26, 3, v24
	v_and_or_b32 v24, v121, 7, v26
	v_lshlrev_b32_e32 v24, 3, v24
	global_load_dwordx2 v[24:25], v24, s[42:43]
	v_and_or_b32 v26, v27, 7, v26
	v_lshlrev_b32_e32 v31, 3, v26
	global_load_dwordx2 v[200:201], v31, s[42:43]
	s_waitcnt vmcnt(0)
	v_pk_mul_f32 v[26:27], v[20:21], v[24:25] op_sel:[1,1] op_sel_hi:[0,1]
	v_pk_mul_f32 v[34:35], v[20:21], v[24:25]
	v_pk_fma_f32 v[20:21], v[20:21], v[24:25], v[26:27] op_sel_hi:[1,0,1]
	v_mul_f32_e32 v20, v23, v201
	v_pk_fma_f32 v[36:37], v[22:23], v[200:201], v[20:21] op_sel_hi:[1,1,0] neg_lo:[0,0,1] neg_hi:[0,0,1]
	v_mul_f32_e32 v20, v22, v201
	v_pk_fma_f32 v[24:25], v[22:23], v[200:201], v[20:21] op_sel:[1,0,0] op_sel_hi:[0,1,0]
	v_sub_f32_e32 v20, v34, v26
	v_mov_b32_e32 v22, v36
	v_mov_b32_e32 v23, v24
.LBB0_2587:
	s_or_b64 exec, exec, s[64:65]
	v_cvt_pk_bf16_f32 v20, v20, v21
	v_cvt_pk_bf16_f32 v21, v22, v23
	global_store_dwordx2 v[28:29], v[20:21], off offset:256
	s_and_b64 s[4:5], s[16:17], s[18:19]
	v_mov_b32_e32 v20, v216
	v_pk_mul_f32 v[18:19], v[18:19], v[20:21] op_sel_hi:[1,0]
	v_pk_mul_f32 v[16:17], v[16:17], v[20:21] op_sel_hi:[1,0]
	s_and_saveexec_b64 s[0:1], s[4:5]
	s_cbranch_execz .LBB0_2589
	v_and_or_b32 v20, v116, 7, v30
	v_lshlrev_b32_e32 v20, 3, v20
	global_load_dwordx2 v[20:21], v20, s[42:43]
	v_add_u32_e32 v22, 1, v116
	v_and_or_b32 v22, v22, 7, v30
	v_lshlrev_b32_e32 v26, 3, v22
	global_load_dwordx2 v[200:201], v26, s[42:43]
	s_waitcnt vmcnt(0)
	v_pk_mul_f32 v[22:23], v[16:17], v[20:21] op_sel:[1,1] op_sel_hi:[0,1]
	v_pk_mul_f32 v[24:25], v[16:17], v[20:21]
	v_pk_fma_f32 v[16:17], v[16:17], v[20:21], v[22:23] op_sel_hi:[1,0,1]
	v_mul_f32_e32 v16, v19, v201
	v_pk_fma_f32 v[26:27], v[18:19], v[200:201], v[16:17] op_sel_hi:[1,1,0] neg_lo:[0,0,1] neg_hi:[0,0,1]
	v_mul_f32_e32 v16, v18, v201
	v_pk_fma_f32 v[20:21], v[18:19], v[200:201], v[16:17] op_sel:[1,0,0] op_sel_hi:[0,1,0]
	v_sub_f32_e32 v16, v24, v22
	v_mov_b32_e32 v18, v26
	v_mov_b32_e32 v19, v20
.LBB0_2589:
	s_or_b64 exec, exec, s[0:1]
	v_cvt_pk_bf16_f32 v16, v16, v17
	v_cvt_pk_bf16_f32 v17, v18, v19
	v_add_u32_e32 v22, 0xb0, v178
	global_store_dwordx2 v[28:29], v[16:17], off offset:288
	v_lshlrev_b32_e32 v16, 1, v22
	v_ashrrev_i32_e32 v17, 31, v16
	v_lshl_add_u64 v[16:17], v[16:17], 2, s[40:41]
	global_load_dword v18, v[16:17], off
	v_mul_hi_i32 v19, v22, s79
	v_lshrrev_b32_e32 v20, 31, v19
	v_ashrrev_i32_e32 v19, 11, v19
	v_add_u32_e32 v19, v19, v20
	v_mul_i32_i24_e32 v19, 0x2100, v19
	v_sub_u32_e32 v23, v22, v19
	v_cmp_lt_i32_e64 s[18:19], s80, v23
	v_add_u32_e32 v19, 0xffffff00, v23
	v_and_b32_e32 v20, 63, v23
	v_lshrrev_b32_e32 v21, 6, v19
	s_and_b64 s[4:5], vcc, s[18:19]
	s_waitcnt vmcnt(0)
	v_mul_f32_e32 v18, 0x3dd105ec, v18
	v_mul_f32_e32 v24, 0x3fb8aa3b, v18
	v_mov_b32_e32 v217, v24
	v_pk_mul_f32 v[18:19], v[14:15], v[24:25] op_sel_hi:[1,0]
	v_pk_mul_f32 v[14:15], v[12:13], v[24:25] op_sel_hi:[1,0]
	s_and_saveexec_b64 s[0:1], s[4:5]
	s_cbranch_execz .LBB0_2591
	v_cmp_gt_u32_e32 vcc, 16, v179
	s_nop 1
	v_cndmask_b32_e32 v12, v20, v21, vcc
	v_lshlrev_b32_e32 v24, 3, v12
	v_and_or_b32 v12, v180, 7, v24
	v_lshlrev_b32_e32 v12, 3, v12
	global_load_dwordx2 v[12:13], v12, s[42:43]
	v_and_or_b32 v24, v180, 6, v24
	v_lshlrev_b32_e32 v28, 3, v24
	global_load_dwordx2 v[200:201], v28, s[42:43] offset:8
	s_waitcnt vmcnt(0)
	v_pk_mul_f32 v[24:25], v[14:15], v[12:13] op_sel:[1,1] op_sel_hi:[0,1]
	v_pk_mul_f32 v[26:27], v[14:15], v[12:13]
	v_pk_fma_f32 v[14:15], v[14:15], v[12:13], v[24:25] op_sel_hi:[1,0,1]
	v_mul_f32_e32 v14, v19, v201
	v_pk_fma_f32 v[28:29], v[18:19], v[200:201], v[14:15] op_sel_hi:[1,1,0] neg_lo:[0,0,1] neg_hi:[0,0,1]
	v_mul_f32_e32 v14, v18, v201
	v_pk_fma_f32 v[12:13], v[18:19], v[200:201], v[14:15] op_sel:[1,0,0] op_sel_hi:[0,1,0]
	v_sub_f32_e32 v14, v26, v24
	v_mov_b32_e32 v18, v28
	v_mov_b32_e32 v19, v12
.LBB0_2591:
	s_or_b64 exec, exec, s[0:1]
	v_mov_b64_e32 v[12:13], s[94:95]
	v_mad_i64_i32 v[12:13], s[0:1], v22, s81, v[12:13]
	v_lshl_add_u64 v[12:13], v[140:141], 1, v[12:13]
	v_cvt_pk_bf16_f32 v14, v14, v15
	v_cvt_pk_bf16_f32 v15, v18, v19
	global_store_dwordx2 v[12:13], v[14:15], off
	v_lshlrev_b32_e32 v14, 3, v23
	v_and_b32_e32 v14, 0x1f8, v14
	s_and_b64 s[4:5], s[12:13], s[18:19]
	v_mov_b32_e32 v18, v217
	v_pk_mul_f32 v[10:11], v[10:11], v[18:19] op_sel_hi:[1,0]
	v_pk_mul_f32 v[8:9], v[8:9], v[18:19] op_sel_hi:[1,0]
	s_and_saveexec_b64 s[0:1], s[4:5]
	s_cbranch_execz .LBB0_2593
	v_and_or_b32 v15, v126, 7, v14
	v_lshlrev_b32_e32 v15, 3, v15
	global_load_dwordx2 v[18:19], v15, s[42:43]
	v_add_u32_e32 v15, 1, v126
	v_and_or_b32 v15, v15, 7, v14
	v_lshlrev_b32_e32 v15, 3, v15
	global_load_dwordx2 v[200:201], v15, s[42:43]
	s_waitcnt vmcnt(0)
	v_pk_mul_f32 v[22:23], v[8:9], v[18:19] op_sel:[1,1] op_sel_hi:[0,1]
	v_pk_mul_f32 v[24:25], v[8:9], v[18:19]
	v_pk_fma_f32 v[8:9], v[8:9], v[18:19], v[22:23] op_sel_hi:[1,0,1]
	v_mul_f32_e32 v8, v11, v201
	v_pk_fma_f32 v[26:27], v[10:11], v[200:201], v[8:9] op_sel_hi:[1,1,0] neg_lo:[0,0,1] neg_hi:[0,0,1]
	v_mul_f32_e32 v8, v10, v201
	v_pk_fma_f32 v[18:19], v[10:11], v[200:201], v[8:9] op_sel:[1,0,0] op_sel_hi:[0,1,0]
	v_sub_f32_e32 v8, v24, v22
	v_mov_b32_e32 v10, v26
	v_mov_b32_e32 v11, v18
.LBB0_2593:
	s_or_b64 exec, exec, s[0:1]
	v_cvt_pk_bf16_f32 v8, v8, v9
	v_cvt_pk_bf16_f32 v9, v10, v11
	global_store_dwordx2 v[12:13], v[8:9], off offset:32
	s_and_b64 s[4:5], s[14:15], s[18:19]
	v_mov_b32_e32 v8, v217
	v_pk_mul_f32 v[6:7], v[6:7], v[8:9] op_sel_hi:[1,0]
	v_pk_mul_f32 v[4:5], v[4:5], v[8:9] op_sel_hi:[1,0]
	s_and_saveexec_b64 s[0:1], s[4:5]
	s_cbranch_execz .LBB0_2595
	v_cmp_gt_u32_e32 vcc, 16, v120
	v_add_u32_e32 v11, 1, v121
	s_nop 0
	v_cndmask_b32_e32 v8, v20, v21, vcc
	v_lshlrev_b32_e32 v10, 3, v8
	v_and_or_b32 v8, v121, 7, v10
	v_lshlrev_b32_e32 v8, 3, v8
	global_load_dwordx2 v[8:9], v8, s[42:43]
	v_and_or_b32 v10, v11, 7, v10
	v_lshlrev_b32_e32 v15, 3, v10
	global_load_dwordx2 v[200:201], v15, s[42:43]
	s_waitcnt vmcnt(0)
	v_pk_mul_f32 v[10:11], v[4:5], v[8:9] op_sel:[1,1] op_sel_hi:[0,1]
	v_pk_mul_f32 v[18:19], v[4:5], v[8:9]
	v_pk_fma_f32 v[4:5], v[4:5], v[8:9], v[10:11] op_sel_hi:[1,0,1]
	v_mul_f32_e32 v4, v7, v201
	v_pk_fma_f32 v[20:21], v[6:7], v[200:201], v[4:5] op_sel_hi:[1,1,0] neg_lo:[0,0,1] neg_hi:[0,0,1]
	v_mul_f32_e32 v4, v6, v201
	v_pk_fma_f32 v[8:9], v[6:7], v[200:201], v[4:5] op_sel:[1,0,0] op_sel_hi:[0,1,0]
	v_sub_f32_e32 v4, v18, v10
	v_mov_b32_e32 v6, v20
	v_mov_b32_e32 v7, v8
.LBB0_2595:
	s_or_b64 exec, exec, s[0:1]
	v_cvt_pk_bf16_f32 v4, v4, v5
	v_cvt_pk_bf16_f32 v5, v6, v7
	global_store_dwordx2 v[12:13], v[4:5], off offset:256
	s_and_b64 s[4:5], s[16:17], s[18:19]
	v_mov_b32_e32 v4, v217
	v_pk_mul_f32 v[2:3], v[2:3], v[4:5] op_sel_hi:[1,0]
	v_pk_mul_f32 v[0:1], v[0:1], v[4:5] op_sel_hi:[1,0]
	s_and_saveexec_b64 s[0:1], s[4:5]
	s_cbranch_execz .LBB0_2597
	v_and_or_b32 v4, v116, 7, v14
	v_lshlrev_b32_e32 v4, 3, v4
	global_load_dwordx2 v[4:5], v4, s[42:43]
	v_add_u32_e32 v6, 1, v116
	v_and_or_b32 v6, v6, 7, v14
	v_lshlrev_b32_e32 v10, 3, v6
	global_load_dwordx2 v[200:201], v10, s[42:43]
	s_waitcnt vmcnt(0)
	v_pk_mul_f32 v[6:7], v[0:1], v[4:5] op_sel:[1,1] op_sel_hi:[0,1]
	v_pk_mul_f32 v[8:9], v[0:1], v[4:5]
	v_pk_fma_f32 v[0:1], v[0:1], v[4:5], v[6:7] op_sel_hi:[1,0,1]
	v_mul_f32_e32 v0, v3, v201
	v_pk_fma_f32 v[10:11], v[2:3], v[200:201], v[0:1] op_sel_hi:[1,1,0] neg_lo:[0,0,1] neg_hi:[0,0,1]
	v_mul_f32_e32 v0, v2, v201
	v_pk_fma_f32 v[4:5], v[2:3], v[200:201], v[0:1] op_sel:[1,0,0] op_sel_hi:[0,1,0]
	v_sub_f32_e32 v0, v8, v6
	v_mov_b32_e32 v2, v10
	v_mov_b32_e32 v3, v4
